# v12 + branch-A K/V LDS-DMA addressing via SGPR base (vcc pair) + 32-bit VGPR offset instead of 64-bit VALU adds
# speedup vs baseline: 1.0101x; 1.0070x over previous
; #define VRD_(S, I) do { vl[S] = vtr(vp + v_rd_off((I) & 3, (I) >> 2, 0)); vh[S] = vtr(vp + v_rd_off((I) & 3, (I) >> 2, 1)); } while (0)
; template <int DK, bool NOMAX> ...
;     ...
; #pragma unroll
;   for (int i = 0; i < 16; ++i) {
;     if (i + 2 < 16) VRD_((i + 2) % 3, i + 2);
;     if (i == 1) { if (dk) __builtin_amdgcn_global_load_lds((const unsigned*)gk0, lk, 16, 0, 0); }
;     if (i == 3) { if constexpr (DK == 128) { if (dk) __builtin_amdgcn_global_load_lds((const unsigned*)gk1, (lds_up)((lds_cp)lk + 8192), 16, 0, 0); } }
;     if (i == 5) { if (dv) __builtin_amdgcn_global_load_lds((const unsigned*)gv0, lv, 16, 0, 0); }
;     if (i == 7) { if (dv) __builtin_amdgcn_global_load_lds((const unsigned*)gv1, (lds_up)((lds_cp)lv + 8192), 16, 0, 0); }
.LBB0_224:
	s_or_b64 exec, exec, s[4:5]
	s_add_i32 s97, s97, 2
	s_cmpk_gt_u32 s97, 0x7c
	s_cselect_b64 s[18:19], -1, 0
	ds_read_b64_tr_b16 v[80:81], v213 offset:1024
	ds_read_b64_tr_b16 v[82:83], v213 offset:3072
	s_waitcnt lgkmcnt(4)
	v_mfma_f32_32x32x16_bf16 v[16:31], v[96:99], v[104:107], v[16:31]
	v_exp_f32_e32 v128, v128
	v_exp_f32_e32 v112, v112
	ds_read_b64_tr_b16 v[84:85], v213 offset:1536
	ds_read_b64_tr_b16 v[86:87], v213 offset:3584
	s_and_b64 vcc, exec, s[18:19]
	s_cbranch_vccnz .LBB0_226
	s_add_u32 vcc_lo, s0, s28
	s_addc_u32 vcc_hi, s1, s29
	s_and_b32 s4, s63, 0xc000
	s_add_i32 m0, s3, s4
	s_nop 0
	global_load_lds_dwordx4 v162, vcc
; template <int DK, bool NOMAX> ...
;     ...
; #pragma unroll
;   for (int i = 0; i < 16; ++i) {
;     if (i + 2 < 16) VRD_((i + 2) % 3, i + 2);
;     if (i == 1) { if (dk) __builtin_amdgcn_global_load_lds((const unsigned*)gk0, lk, 16, 0, 0); }
;     if (i == 3) { if constexpr (DK == 128) { if (dk) __builtin_amdgcn_global_load_lds((const unsigned*)gk1, (lds_up)((lds_cp)lk + 8192), 16, 0, 0); } }
;     if (i == 5) { if (dv) __builtin_amdgcn_global_load_lds((const unsigned*)gv0, lv, 16, 0, 0); }
;     if (i == 7) { if (dv) __builtin_amdgcn_global_load_lds((const unsigned*)gv1, (lds_up)((lds_cp)lv + 8192), 16, 0, 0); }
;     if (i == 12 || i == 13) { const int cb_ = ((i - 12) * 16 + hi * 8) * 2;
;       if constexpr (DK == 128) { kf[i - 12][0] = *reinterpret_cast<const bf16x8*>(Kn + KSWZ128(r32, cb_)); kf[i - 12][1] = *reinterpret_cast<const bf16x8*>(Kn + KSWZ128(32 + r32, cb_)); }
;       else { kf[i - 12][0] = *reinterpret_cast<const bf16x8*>(Kn + KSWZ64(r32, cb_)); kf[i - 12][1] = *reinterpret_cast<const bf16x8*>(Kn + KSWZ64(32 + r32, cb_)); } }
;     SBAR();
;     o[i & 3] = __builtin_amdgcn_mfma_f32_32x32x16_bf16(pa[i >> 2], VFR_(i % 3), o[i & 3], 0, 0, 0);
;     if constexpr (NOMAX) { c0[i] = __builtin_amdgcn_exp2f(c0[i]); c1[i] = __builtin_amdgcn_exp2f(c1[i]); if (i > 0) { psa += c0[i - 1]; psb += c1[i - 1]; } PIN(c0); PIN(c1); PIN(psa); PIN(psb); }
;     else {
;     if (i == 0) { ma = max3f(c0[0], c0[1], c1[0]); mb = max3f(c0[2], c0[3], c1[1]); ma = max3f(ma, c1[2], c1[3]); }
;     if (i >= 1 && i <= 3) { const int r = 4 * i; ma = max3f(ma, c0[r], c0[r + 1]); mb = max3f(mb, c0[r + 2], c0[r + 3]); ma = max3f(ma, c1[r], c1[r + 1]); mb = max3f(mb, c1[r + 2], c1[r + 3]); }
;     if (i == 4) { float pmax = fmaxf(ma, mb);
;       { auto rr = __builtin_amdgcn_permlane32_swap(__float_as_uint(pmax), __float_as_uint(pmax), false, false);
;         pmax = fmaxf(__uint_as_float(rr[0]), __uint_as_float(rr[1])); }
;       pmax += cb;
;       const bool keep = __all(pmax - m_reg <= THR2);
;       const float mn = keep ? m_reg : fmaxf(m_reg, pmax);
;       alpha = __builtin_amdgcn_exp2f(m_reg - mn); m_reg = mn; mnC = cb - mn; }
;     if (i >= 5 && i <= 8) { const int r = 4 * (i - 5);
; #pragma unroll
;       for (int q = 0; q < 4; ++q) { c0[r + q] += mnC; c1[r + q] += mnC; } }
;     if (i >= 9) { const int r0 = (i - 9) * 2 + (i > 14 ? 1 : 0), n = i >= 14 ? 3 : 2;
.LBB0_226:
	v_sub_f32_e32 v0, v212, v215
	v_exp_f32_e32 v0, v0
	s_add_i32 s4, s63, 0xffff8000
	s_and_b32 s4, s4, 0xc000
	s_add_i32 s94, s4, 0
	s_waitcnt lgkmcnt(4)
	v_mfma_f32_32x32x16_bf16 v[32:47], v[96:99], v[100:103], v[32:47]
	v_exp_f32_e32 v129, v129
	v_exp_f32_e32 v113, v113
	ds_read_b64_tr_b16 v[88:89], v213 offset:4096
	ds_read_b64_tr_b16 v[90:91], v213 offset:6144
	s_waitcnt lgkmcnt(4)
	v_mfma_f32_32x32x16_bf16 v[48:63], v[96:99], v[80:83], v[48:63]
	v_exp_f32_e32 v130, v130
	v_exp_f32_e32 v114, v114
	v_add_f32_e32 v100, v113, v112
	v_add_f32_e32 v101, v129, v128
	ds_read_b64_tr_b16 v[80:81], v213 offset:4608
	ds_read_b64_tr_b16 v[82:83], v213 offset:6656
	s_waitcnt lgkmcnt(4)
	v_mfma_f32_32x32x16_bf16 v[64:79], v[96:99], v[84:87], v[64:79]
	v_exp_f32_e32 v131, v131
	v_exp_f32_e32 v115, v115
	v_add_f32_e32 v96, v114, v100
	v_add_f32_e32 v97, v130, v101
	ds_read_b64_tr_b16 v[84:85], v213 offset:5120
	ds_read_b64_tr_b16 v[86:87], v213 offset:7168
	s_waitcnt lgkmcnt(4)
	v_mfma_f32_32x32x16_bf16 v[16:31], v[10:13], v[88:91], v[16:31]
	v_exp_f32_e32 v132, v132
	v_exp_f32_e32 v116, v116
	v_add_f32_e32 v96, v115, v96
	v_add_f32_e32 v97, v131, v97
	s_add_u32 vcc_lo, s0, s30
	s_addc_u32 vcc_hi, s1, s31
	s_add_i32 s4, s62, s58
	s_mov_b32 m0, s4
	ds_read_b64_tr_b16 v[88:89], v213 offset:5632
	ds_read_b64_tr_b16 v[90:91], v213 offset:7680
	global_load_lds_dwordx4 v160, vcc
	s_waitcnt lgkmcnt(4)
	v_mfma_f32_32x32x16_bf16 v[32:47], v[10:13], v[80:83], v[32:47]
	v_exp_f32_e32 v133, v133
	v_exp_f32_e32 v117, v117
	v_add_f32_e32 v92, v116, v96
	v_add_f32_e32 v93, v132, v97
	ds_read_b64_tr_b16 v[80:81], v213 offset:8192
	ds_read_b64_tr_b16 v[82:83], v213 offset:10240
	s_waitcnt lgkmcnt(4)
	v_mfma_f32_32x32x16_bf16 v[48:63], v[10:13], v[84:87], v[48:63]
	v_exp_f32_e32 v134, v134
	v_exp_f32_e32 v118, v118
	v_add_f32_e32 v92, v117, v92
	v_add_f32_e32 v93, v133, v93
	s_add_i32 m0, s4, 0x2000
	ds_read_b64_tr_b16 v[84:85], v213 offset:8704
	ds_read_b64_tr_b16 v[86:87], v213 offset:10752
	global_load_lds_dwordx4 v14, vcc
	s_waitcnt lgkmcnt(4)
	v_mfma_f32_32x32x16_bf16 v[64:79], v[10:13], v[88:91], v[64:79]
	v_exp_f32_e32 v135, v135
	v_exp_f32_e32 v119, v119
	v_add_f32_e32 v88, v118, v92
	v_add_f32_e32 v89, v134, v93
	ds_read_b64_tr_b16 v[10:11], v213 offset:9216
	ds_read_b64_tr_b16 v[12:13], v213 offset:11264
	s_waitcnt lgkmcnt(4)
	v_mfma_f32_32x32x16_bf16 v[16:31], v[6:9], v[80:83], v[16:31]
	v_exp_f32_e32 v136, v136
	v_exp_f32_e32 v120, v120
	v_add_f32_e32 v88, v119, v88
	v_add_f32_e32 v89, v135, v89
	ds_read_b64_tr_b16 v[80:81], v213 offset:9728
	ds_read_b64_tr_b16 v[82:83], v213 offset:11776
	s_waitcnt lgkmcnt(4)
	v_mfma_f32_32x32x16_bf16 v[32:47], v[6:9], v[84:87], v[32:47]
	v_exp_f32_e32 v137, v137
	v_exp_f32_e32 v121, v121
	v_add_f32_e32 v84, v120, v88
	v_add_f32_e32 v85, v136, v89
	ds_read_b64_tr_b16 v[88:89], v213 offset:12288
	ds_read_b64_tr_b16 v[90:91], v213 offset:14336
	s_waitcnt lgkmcnt(4)
	v_mfma_f32_32x32x16_bf16 v[48:63], v[6:9], v[10:13], v[48:63]
	v_exp_f32_e32 v138, v138
	v_exp_f32_e32 v122, v122
	v_add_f32_e32 v10, v121, v84
	v_add_f32_e32 v11, v137, v85
	ds_read_b64_tr_b16 v[92:93], v213 offset:12800
	ds_read_b64_tr_b16 v[94:95], v213 offset:14848
	s_waitcnt lgkmcnt(4)
	v_mfma_f32_32x32x16_bf16 v[64:79], v[6:9], v[80:83], v[64:79]
	v_exp_f32_e32 v139, v139
	v_exp_f32_e32 v123, v123
	v_add_f32_e32 v6, v122, v10
	v_add_f32_e32 v7, v138, v11
	v_add_u32_e32 v8, s94, v209
	ds_read_b64_tr_b16 v[96:97], v213 offset:13312
	ds_read_b64_tr_b16 v[98:99], v213 offset:15360
	ds_read_b128 v[80:83], v8
	ds_read_b128 v[84:87], v8 offset:4096
	s_waitcnt lgkmcnt(6)
	v_mfma_f32_32x32x16_bf16 v[16:31], v[2:5], v[88:91], v[16:31]
	v_exp_f32_e32 v140, v140
	v_exp_f32_e32 v124, v124
	v_add_f32_e32 v100, v123, v6
	v_add_f32_e32 v101, v139, v7
	v_add_u32_e32 v10, s94, v210
	ds_read_b64_tr_b16 v[88:89], v213 offset:13824
	ds_read_b64_tr_b16 v[90:91], v213 offset:15872
	ds_read_b128 v[6:9], v10
	ds_read_b128 v[10:13], v10 offset:4096
	s_waitcnt lgkmcnt(8)
	v_mfma_f32_32x32x16_bf16 v[32:47], v[2:5], v[92:95], v[32:47]
	v_exp_f32_e32 v141, v141
	v_exp_f32_e32 v125, v125
	v_add_f32_e32 v92, v124, v100
	v_add_f32_e32 v93, v140, v101
	s_waitcnt lgkmcnt(6)
	v_mfma_f32_32x32x16_bf16 v[48:63], v[2:5], v[96:99], v[48:63]
	v_exp_f32_e32 v142, v142
	v_exp_f32_e32 v126, v126
	v_add_f32_e32 v92, v125, v92
	v_add_f32_e32 v93, v141, v93
	s_waitcnt lgkmcnt(2)
	v_mfma_f32_32x32x16_bf16 v[64:79], v[2:5], v[88:91], v[64:79]
	v_exp_f32_e32 v143, v143
	v_exp_f32_e32 v127, v127
	v_add_f32_e32 v2, v126, v92
	v_add_f32_e32 v3, v142, v93
	s_nop 0
	v_add_f32_e32 v3, v143, v3
	v_add_f32_e32 v2, v127, v2
	v_add_f32_e32 v213, v3, v2
	v_mov_b32_e32 v214, v213
	s_nop 1
	v_permlane32_swap_b32_e32 v213, v214
	v_cmp_neq_f32_e32 vcc, 1.0, v0
	s_cbranch_vccz .LBB0_230
	s_and_saveexec_b64 s[4:5], s[46:47]
	ds_write_b32 v188, v0 offset:128
	s_or_b64 exec, exec, s[4:5]
	s_waitcnt lgkmcnt(0)
	v_add_u32_e32 v96, s2, v171
	ds_read_b128 v[2:5], v96 offset:224
	ds_read_b128 v[88:91], v96 offset:192
	ds_read_b128 v[92:95], v96 offset:160
	ds_read_b128 v[96:99], v96 offset:128
	s_waitcnt lgkmcnt(0)
	v_pk_mul_f32 v[28:29], v[28:29], v[2:3]
	v_pk_mul_f32 v[24:25], v[24:25], v[88:89]
	v_pk_mul_f32 v[20:21], v[20:21], v[92:93]
	v_pk_mul_f32 v[30:31], v[30:31], v[4:5]
	v_pk_mul_f32 v[26:27], v[26:27], v[90:91]
	v_pk_mul_f32 v[22:23], v[22:23], v[94:95]
	v_pk_mul_f32 v[18:19], v[18:19], v[98:99]
	v_pk_mul_f32 v[16:17], v[16:17], v[96:97]
	v_pk_mul_f32 v[44:45], v[44:45], v[2:3]
	v_pk_mul_f32 v[40:41], v[40:41], v[88:89]
	v_pk_mul_f32 v[36:37], v[36:37], v[92:93]
	v_pk_mul_f32 v[46:47], v[46:47], v[4:5]
	v_pk_mul_f32 v[42:43], v[42:43], v[90:91]
	v_pk_mul_f32 v[38:39], v[38:39], v[94:95]
	v_pk_mul_f32 v[34:35], v[34:35], v[98:99]
	v_pk_mul_f32 v[32:33], v[32:33], v[96:97]
	v_pk_mul_f32 v[60:61], v[60:61], v[2:3]
	v_pk_mul_f32 v[56:57], v[56:57], v[88:89]
	v_pk_mul_f32 v[52:53], v[52:53], v[92:93]
	v_pk_mul_f32 v[62:63], v[62:63], v[4:5]
	v_pk_mul_f32 v[58:59], v[58:59], v[90:91]
	v_pk_mul_f32 v[54:55], v[54:55], v[94:95]
	v_pk_mul_f32 v[50:51], v[50:51], v[98:99]
	v_pk_mul_f32 v[48:49], v[48:49], v[96:97]
	v_pk_mul_f32 v[76:77], v[76:77], v[2:3]
	v_pk_mul_f32 v[72:73], v[72:73], v[88:89]
	v_pk_mul_f32 v[68:69], v[68:69], v[92:93]
	v_pk_mul_f32 v[78:79], v[78:79], v[4:5]
	v_pk_mul_f32 v[74:75], v[74:75], v[90:91]
	v_pk_mul_f32 v[70:71], v[70:71], v[94:95]
	v_pk_mul_f32 v[66:67], v[66:67], v[98:99]
	v_pk_mul_f32 v[64:65], v[64:65], v[96:97]

; #define VRD_(S, I) do { vl[S] = vtr(vp + v_rd_off((I) & 3, (I) >> 2, 0)); vh[S] = vtr(vp + v_rd_off((I) & 3, (I) >> 2, 1)); } while (0)
; template <int DK, bool NOMAX> ...
;     ...
; #pragma unroll
;   for (int i = 0; i < 16; ++i) {
;     if (i + 2 < 16) VRD_((i + 2) % 3, i + 2);
;     if (i == 1) { if (dk) __builtin_amdgcn_global_load_lds((const unsigned*)gk0, lk, 16, 0, 0); }
;     if (i == 3) { if constexpr (DK == 128) { if (dk) __builtin_amdgcn_global_load_lds((const unsigned*)gk1, (lds_up)((lds_cp)lk + 8192), 16, 0, 0); } }
;     if (i == 5) { if (dv) __builtin_amdgcn_global_load_lds((const unsigned*)gv0, lv, 16, 0, 0); }
;     if (i == 7) { if (dv) __builtin_amdgcn_global_load_lds((const unsigned*)gv1, (lds_up)((lds_cp)lv + 8192), 16, 0, 0); }
.LBB0_238:
	s_or_b64 exec, exec, s[4:5]
	s_cmpk_gt_u32 s97, 0x7b
	s_cselect_b64 s[4:5], -1, 0
	ds_read_b64_tr_b16 v[112:113], v217 offset:1024
	ds_read_b64_tr_b16 v[114:115], v217 offset:3072
	s_waitcnt lgkmcnt(4)
	v_mfma_f32_32x32x16_bf16 v[16:31], v[128:131], v[136:139], v[16:31]
	v_exp_f32_e32 v96, v96
	v_exp_f32_e32 v80, v80
	ds_read_b64_tr_b16 v[116:117], v217 offset:1536
	ds_read_b64_tr_b16 v[118:119], v217 offset:3584
	s_and_b64 vcc, exec, s[4:5]
	s_cbranch_vccnz .LBB0_240
	s_add_u32 vcc_lo, s0, s34
	s_addc_u32 vcc_hi, s1, s35
	s_add_i32 m0, s3, s59
	s_nop 0
	global_load_lds_dwordx4 v162, vcc
; template <int DK, bool NOMAX> ...
;     ...
; #pragma unroll
;   for (int i = 0; i < 16; ++i) {
;     if (i + 2 < 16) VRD_((i + 2) % 3, i + 2);
;     if (i == 1) { if (dk) __builtin_amdgcn_global_load_lds((const unsigned*)gk0, lk, 16, 0, 0); }
;     if (i == 3) { if constexpr (DK == 128) { if (dk) __builtin_amdgcn_global_load_lds((const unsigned*)gk1, (lds_up)((lds_cp)lk + 8192), 16, 0, 0); } }
;     if (i == 5) { if (dv) __builtin_amdgcn_global_load_lds((const unsigned*)gv0, lv, 16, 0, 0); }
;     if (i == 7) { if (dv) __builtin_amdgcn_global_load_lds((const unsigned*)gv1, (lds_up)((lds_cp)lv + 8192), 16, 0, 0); }
;     if (i == 12 || i == 13) { const int cb_ = ((i - 12) * 16 + hi * 8) * 2;
;       if constexpr (DK == 128) { kf[i - 12][0] = *reinterpret_cast<const bf16x8*>(Kn + KSWZ128(r32, cb_)); kf[i - 12][1] = *reinterpret_cast<const bf16x8*>(Kn + KSWZ128(32 + r32, cb_)); }
;       else { kf[i - 12][0] = *reinterpret_cast<const bf16x8*>(Kn + KSWZ64(r32, cb_)); kf[i - 12][1] = *reinterpret_cast<const bf16x8*>(Kn + KSWZ64(32 + r32, cb_)); } }
;     SBAR();
;     o[i & 3] = __builtin_amdgcn_mfma_f32_32x32x16_bf16(pa[i >> 2], VFR_(i % 3), o[i & 3], 0, 0, 0);
;     if constexpr (NOMAX) { c0[i] = __builtin_amdgcn_exp2f(c0[i]); c1[i] = __builtin_amdgcn_exp2f(c1[i]); if (i > 0) { psa += c0[i - 1]; psb += c1[i - 1]; } PIN(c0); PIN(c1); PIN(psa); PIN(psb); }
;     else {
;     if (i == 0) { ma = max3f(c0[0], c0[1], c1[0]); mb = max3f(c0[2], c0[3], c1[1]); ma = max3f(ma, c1[2], c1[3]); }
;     if (i >= 1 && i <= 3) { const int r = 4 * i; ma = max3f(ma, c0[r], c0[r + 1]); mb = max3f(mb, c0[r + 2], c0[r + 3]); ma = max3f(ma, c1[r], c1[r + 1]); mb = max3f(mb, c1[r + 2], c1[r + 3]); }
;     if (i == 4) { float pmax = fmaxf(ma, mb);
;       { auto rr = __builtin_amdgcn_permlane32_swap(__float_as_uint(pmax), __float_as_uint(pmax), false, false);
;         pmax = fmaxf(__uint_as_float(rr[0]), __uint_as_float(rr[1])); }
;       pmax += cb;
;       const bool keep = __all(pmax - m_reg <= THR2);
;       const float mn = keep ? m_reg : fmaxf(m_reg, pmax);
;       alpha = __builtin_amdgcn_exp2f(m_reg - mn); m_reg = mn; mnC = cb - mn; }
;     if (i >= 5 && i <= 8) { const int r = 4 * (i - 5);
; #pragma unroll
;       for (int q = 0; q < 4; ++q) { c0[r + q] += mnC; c1[r + q] += mnC; } }
;     if (i >= 9) { const int r0 = (i - 9) * 2 + (i > 14 ? 1 : 0), n = i >= 14 ? 3 : 2;
.LBB0_240:
	v_sub_f32_e32 v120, v215, v212
	v_exp_f32_e32 v120, v120
	s_add_i32 s59, s63, 0xffffc000
	s_and_b32 s59, s59, 0xc000
	s_add_i32 s59, s59, 0
	s_waitcnt lgkmcnt(4)
	v_mfma_f32_32x32x16_bf16 v[32:47], v[128:131], v[132:135], v[32:47]
	v_exp_f32_e32 v97, v97
	v_exp_f32_e32 v81, v81
	ds_read_b64_tr_b16 v[122:123], v217 offset:4096
	ds_read_b64_tr_b16 v[124:125], v217 offset:6144
	s_waitcnt lgkmcnt(4)
	v_mfma_f32_32x32x16_bf16 v[48:63], v[128:131], v[112:115], v[48:63]
	v_exp_f32_e32 v98, v98
	v_exp_f32_e32 v82, v82
	v_add_f32_e32 v132, v81, v80
	v_add_f32_e32 v121, v97, v96
	ds_read_b64_tr_b16 v[112:113], v217 offset:4608
	ds_read_b64_tr_b16 v[114:115], v217 offset:6656
	s_waitcnt lgkmcnt(4)
	v_mfma_f32_32x32x16_bf16 v[64:79], v[128:131], v[116:119], v[64:79]
	v_exp_f32_e32 v99, v99
	v_exp_f32_e32 v83, v83
	v_add_f32_e32 v128, v82, v132
	v_add_f32_e32 v121, v98, v121
	ds_read_b64_tr_b16 v[116:117], v217 offset:5120
	ds_read_b64_tr_b16 v[118:119], v217 offset:7168
	s_waitcnt lgkmcnt(4)
	v_mfma_f32_32x32x16_bf16 v[16:31], v[10:13], v[122:125], v[16:31]
	v_exp_f32_e32 v100, v100
	v_exp_f32_e32 v84, v84
	v_add_f32_e32 v128, v83, v128
	v_add_f32_e32 v121, v99, v121
	s_add_u32 vcc_lo, s0, s36
	s_addc_u32 vcc_hi, s1, s37
	s_add_i32 s94, s62, s96
	s_mov_b32 m0, s94
	ds_read_b64_tr_b16 v[122:123], v217 offset:5632
	ds_read_b64_tr_b16 v[124:125], v217 offset:7680
	global_load_lds_dwordx4 v160, vcc
	s_waitcnt lgkmcnt(4)
	v_mfma_f32_32x32x16_bf16 v[32:47], v[10:13], v[112:115], v[32:47]
	v_exp_f32_e32 v101, v101
	v_exp_f32_e32 v85, v85
	v_add_f32_e32 v126, v84, v128
	v_add_f32_e32 v121, v100, v121
	ds_read_b64_tr_b16 v[112:113], v217 offset:8192
	ds_read_b64_tr_b16 v[114:115], v217 offset:10240
	s_waitcnt lgkmcnt(4)
	v_mfma_f32_32x32x16_bf16 v[48:63], v[10:13], v[116:119], v[48:63]
	v_exp_f32_e32 v102, v102
	v_exp_f32_e32 v86, v86
	v_add_f32_e32 v126, v85, v126
	v_add_f32_e32 v121, v101, v121
	s_add_i32 m0, s94, 0x2000
	ds_read_b64_tr_b16 v[116:117], v217 offset:8704
	ds_read_b64_tr_b16 v[118:119], v217 offset:10752
	global_load_lds_dwordx4 v14, vcc
	s_waitcnt lgkmcnt(4)
	v_mfma_f32_32x32x16_bf16 v[64:79], v[10:13], v[122:125], v[64:79]
	v_exp_f32_e32 v103, v103
	v_exp_f32_e32 v87, v87
	v_add_f32_e32 v122, v86, v126
	v_add_f32_e32 v121, v102, v121
	ds_read_b64_tr_b16 v[10:11], v217 offset:9216
	ds_read_b64_tr_b16 v[12:13], v217 offset:11264
	s_waitcnt lgkmcnt(4)
	v_mfma_f32_32x32x16_bf16 v[16:31], v[6:9], v[112:115], v[16:31]
	v_exp_f32_e32 v104, v104
	v_exp_f32_e32 v88, v88
	v_add_f32_e32 v122, v87, v122
	v_add_f32_e32 v121, v103, v121
	ds_read_b64_tr_b16 v[112:113], v217 offset:9728
	ds_read_b64_tr_b16 v[114:115], v217 offset:11776
	s_waitcnt lgkmcnt(4)
	v_mfma_f32_32x32x16_bf16 v[32:47], v[6:9], v[116:119], v[32:47]
	v_exp_f32_e32 v105, v105
	v_exp_f32_e32 v89, v89
	v_add_f32_e32 v116, v88, v122
	v_add_f32_e32 v117, v104, v121
	ds_read_b64_tr_b16 v[122:123], v217 offset:12288
	ds_read_b64_tr_b16 v[124:125], v217 offset:14336
	s_waitcnt lgkmcnt(4)
	v_mfma_f32_32x32x16_bf16 v[48:63], v[6:9], v[10:13], v[48:63]
	v_exp_f32_e32 v106, v106
	v_exp_f32_e32 v90, v90
	v_add_f32_e32 v10, v89, v116
	v_add_f32_e32 v11, v105, v117
	ds_read_b64_tr_b16 v[126:127], v217 offset:12800
	ds_read_b64_tr_b16 v[128:129], v217 offset:14848
	s_waitcnt lgkmcnt(4)
	v_mfma_f32_32x32x16_bf16 v[64:79], v[6:9], v[112:115], v[64:79]
	v_exp_f32_e32 v107, v107
	v_exp_f32_e32 v91, v91
	v_add_f32_e32 v6, v90, v10
	v_add_f32_e32 v7, v106, v11
	v_add_u32_e32 v8, s59, v209
	ds_read_b64_tr_b16 v[130:131], v217 offset:13312
	ds_read_b64_tr_b16 v[132:133], v217 offset:15360
	ds_read_b128 v[116:119], v8
	ds_read_b128 v[112:115], v8 offset:4096
	s_waitcnt lgkmcnt(6)
	v_mfma_f32_32x32x16_bf16 v[16:31], v[2:5], v[122:125], v[16:31]
	v_exp_f32_e32 v108, v108
	v_exp_f32_e32 v92, v92
	v_add_f32_e32 v121, v91, v6
	v_add_f32_e32 v134, v107, v7
	v_add_u32_e32 v6, s59, v210
	ds_read_b64_tr_b16 v[122:123], v217 offset:13824
	ds_read_b64_tr_b16 v[124:125], v217 offset:15872
	ds_read_b128 v[10:13], v6
	ds_read_b128 v[6:9], v6 offset:4096
	s_waitcnt lgkmcnt(8)
	v_mfma_f32_32x32x16_bf16 v[32:47], v[2:5], v[126:129], v[32:47]
	v_exp_f32_e32 v109, v109
	v_exp_f32_e32 v93, v93
	v_add_f32_e32 v121, v92, v121
	v_add_f32_e32 v126, v108, v134
	s_waitcnt lgkmcnt(6)
	v_mfma_f32_32x32x16_bf16 v[48:63], v[2:5], v[130:133], v[48:63]
	v_exp_f32_e32 v110, v110
	v_exp_f32_e32 v94, v94
	v_add_f32_e32 v121, v93, v121
	v_add_f32_e32 v126, v109, v126
	s_waitcnt lgkmcnt(2)
	v_mfma_f32_32x32x16_bf16 v[64:79], v[2:5], v[122:125], v[64:79]
	v_exp_f32_e32 v111, v111
	v_exp_f32_e32 v95, v95
	v_add_f32_e32 v2, v94, v121
	v_add_f32_e32 v3, v110, v126
	s_nop 0
	v_add_f32_e32 v3, v111, v3
	v_add_f32_e32 v2, v95, v2
	v_add_f32_e32 v2, v3, v2
	v_mov_b32_e32 v3, v2
	s_nop 1
	v_permlane32_swap_b32_e32 v2, v3
	v_cmp_neq_f32_e32 vcc, 1.0, v120
	s_cbranch_vccz .LBB0_244
	s_and_saveexec_b64 s[94:95], s[46:47]
	ds_write_b32 v188, v120 offset:128
	s_or_b64 exec, exec, s[94:95]
	s_waitcnt lgkmcnt(0)
	v_add_u32_e32 v4, s2, v171
	ds_read_b128 v[122:125], v4 offset:224
	ds_read_b128 v[126:129], v4 offset:192
	ds_read_b128 v[130:133], v4 offset:160
	ds_read_b128 v[134:137], v4 offset:128
	s_waitcnt lgkmcnt(0)
	v_pk_mul_f32 v[28:29], v[28:29], v[122:123]
	v_pk_mul_f32 v[24:25], v[24:25], v[126:127]
	v_pk_mul_f32 v[20:21], v[20:21], v[130:131]
	v_pk_mul_f32 v[30:31], v[30:31], v[124:125]
	v_pk_mul_f32 v[26:27], v[26:27], v[128:129]
	v_pk_mul_f32 v[22:23], v[22:23], v[132:133]
	v_pk_mul_f32 v[18:19], v[18:19], v[136:137]
	v_pk_mul_f32 v[16:17], v[16:17], v[134:135]
	v_pk_mul_f32 v[44:45], v[44:45], v[122:123]
	v_pk_mul_f32 v[40:41], v[40:41], v[126:127]
	v_pk_mul_f32 v[36:37], v[36:37], v[130:131]
	v_pk_mul_f32 v[46:47], v[46:47], v[124:125]
	v_pk_mul_f32 v[42:43], v[42:43], v[128:129]
	v_pk_mul_f32 v[38:39], v[38:39], v[132:133]
	v_pk_mul_f32 v[34:35], v[34:35], v[136:137]
	v_pk_mul_f32 v[32:33], v[32:33], v[134:135]
	v_pk_mul_f32 v[60:61], v[60:61], v[122:123]
	v_pk_mul_f32 v[56:57], v[56:57], v[126:127]
	v_pk_mul_f32 v[52:53], v[52:53], v[130:131]
	v_pk_mul_f32 v[62:63], v[62:63], v[124:125]
	v_pk_mul_f32 v[58:59], v[58:59], v[128:129]
	v_pk_mul_f32 v[54:55], v[54:55], v[132:133]
	v_pk_mul_f32 v[50:51], v[50:51], v[136:137]
	v_pk_mul_f32 v[48:49], v[48:49], v[134:135]
	v_pk_mul_f32 v[76:77], v[76:77], v[122:123]
	v_pk_mul_f32 v[72:73], v[72:73], v[126:127]
	v_pk_mul_f32 v[68:69], v[68:69], v[130:131]
	v_pk_mul_f32 v[78:79], v[78:79], v[124:125]
	v_pk_mul_f32 v[74:75], v[74:75], v[128:129]
	v_pk_mul_f32 v[70:71], v[70:71], v[132:133]
	v_pk_mul_f32 v[66:67], v[66:67], v[136:137]
	v_pk_mul_f32 v[64:65], v[64:65], v[134:135]

; #define VRD_(S, I) do { vl[S] = vtr(vp + v_rd_off((I) & 3, (I) >> 2, 0)); vh[S] = vtr(vp + v_rd_off((I) & 3, (I) >> 2, 1)); } while (0)
; template <int DK, bool NOMAX> ...
;     ...
; #pragma unroll
;   for (int i = 0; i < 16; ++i) {
;     if (i + 2 < 16) VRD_((i + 2) % 3, i + 2);
;     if (i == 1) { if (dk) __builtin_amdgcn_global_load_lds((const unsigned*)gk0, lk, 16, 0, 0); }
;     if (i == 3) { if constexpr (DK == 128) { if (dk) __builtin_amdgcn_global_load_lds((const unsigned*)gk1, (lds_up)((lds_cp)lk + 8192), 16, 0, 0); } }
;     if (i == 5) { if (dv) __builtin_amdgcn_global_load_lds((const unsigned*)gv0, lv, 16, 0, 0); }
;     if (i == 7) { if (dv) __builtin_amdgcn_global_load_lds((const unsigned*)gv1, (lds_up)((lds_cp)lv + 8192), 16, 0, 0); }
.LBB0_317:
	s_or_b64 exec, exec, s[4:5]
	s_add_i32 s96, s96, 2
	s_cmp_gt_u32 s96, 60
	s_cselect_b64 s[16:17], -1, 0
	ds_read_b64_tr_b16 v[80:81], v213 offset:1024
	ds_read_b64_tr_b16 v[82:83], v213 offset:3072
	s_waitcnt lgkmcnt(4)
	v_mfma_f32_32x32x16_bf16 v[16:31], v[96:99], v[104:107], v[16:31]
	v_exp_f32_e32 v128, v128
	v_exp_f32_e32 v112, v112
	ds_read_b64_tr_b16 v[84:85], v213 offset:1536
	ds_read_b64_tr_b16 v[86:87], v213 offset:3584
	s_and_b64 vcc, exec, s[16:17]
	s_cbranch_vccnz .LBB0_319
	s_add_u32 vcc_lo, s0, s28
	s_addc_u32 vcc_hi, s1, s29
	s_and_b32 s4, s63, 0xc000
	s_add_i32 m0, s3, s4
	s_nop 0
	global_load_lds_dwordx4 v162, vcc
; template <int DK, bool NOMAX> ...
;     ...
; #pragma unroll
;   for (int i = 0; i < 16; ++i) {
;     if (i + 2 < 16) VRD_((i + 2) % 3, i + 2);
;     if (i == 1) { if (dk) __builtin_amdgcn_global_load_lds((const unsigned*)gk0, lk, 16, 0, 0); }
;     if (i == 3) { if constexpr (DK == 128) { if (dk) __builtin_amdgcn_global_load_lds((const unsigned*)gk1, (lds_up)((lds_cp)lk + 8192), 16, 0, 0); } }
;     if (i == 5) { if (dv) __builtin_amdgcn_global_load_lds((const unsigned*)gv0, lv, 16, 0, 0); }
;     if (i == 7) { if (dv) __builtin_amdgcn_global_load_lds((const unsigned*)gv1, (lds_up)((lds_cp)lv + 8192), 16, 0, 0); }
;     if (i == 12 || i == 13) { const int cb_ = ((i - 12) * 16 + hi * 8) * 2;
;       if constexpr (DK == 128) { kf[i - 12][0] = *reinterpret_cast<const bf16x8*>(Kn + KSWZ128(r32, cb_)); kf[i - 12][1] = *reinterpret_cast<const bf16x8*>(Kn + KSWZ128(32 + r32, cb_)); }
;       else { kf[i - 12][0] = *reinterpret_cast<const bf16x8*>(Kn + KSWZ64(r32, cb_)); kf[i - 12][1] = *reinterpret_cast<const bf16x8*>(Kn + KSWZ64(32 + r32, cb_)); } }
;     SBAR();
;     o[i & 3] = __builtin_amdgcn_mfma_f32_32x32x16_bf16(pa[i >> 2], VFR_(i % 3), o[i & 3], 0, 0, 0);
;     if constexpr (NOMAX) { c0[i] = __builtin_amdgcn_exp2f(c0[i]); c1[i] = __builtin_amdgcn_exp2f(c1[i]); if (i > 0) { psa += c0[i - 1]; psb += c1[i - 1]; } PIN(c0); PIN(c1); PIN(psa); PIN(psb); }
;     else {
;     if (i == 0) { ma = max3f(c0[0], c0[1], c1[0]); mb = max3f(c0[2], c0[3], c1[1]); ma = max3f(ma, c1[2], c1[3]); }
;     if (i >= 1 && i <= 3) { const int r = 4 * i; ma = max3f(ma, c0[r], c0[r + 1]); mb = max3f(mb, c0[r + 2], c0[r + 3]); ma = max3f(ma, c1[r], c1[r + 1]); mb = max3f(mb, c1[r + 2], c1[r + 3]); }
;     if (i == 4) { float pmax = fmaxf(ma, mb);
;       { auto rr = __builtin_amdgcn_permlane32_swap(__float_as_uint(pmax), __float_as_uint(pmax), false, false);
;         pmax = fmaxf(__uint_as_float(rr[0]), __uint_as_float(rr[1])); }
;       pmax += cb;
;       const bool keep = __all(pmax - m_reg <= THR2);
;       const float mn = keep ? m_reg : fmaxf(m_reg, pmax);
;       alpha = __builtin_amdgcn_exp2f(m_reg - mn); m_reg = mn; mnC = cb - mn; }
;     if (i >= 5 && i <= 8) { const int r = 4 * (i - 5);
; #pragma unroll
;       for (int q = 0; q < 4; ++q) { c0[r + q] += mnC; c1[r + q] += mnC; } }
;     if (i >= 9) { const int r0 = (i - 9) * 2 + (i > 14 ? 1 : 0), n = i >= 14 ? 3 : 2;
.LBB0_319:
	v_sub_f32_e32 v0, v212, v215
	v_exp_f32_e32 v0, v0
	s_add_i32 s4, s63, 0xffff8000
	s_and_b32 s4, s4, 0xc000
	s_add_i32 s18, s4, 0
	s_waitcnt lgkmcnt(4)
	v_mfma_f32_32x32x16_bf16 v[32:47], v[96:99], v[100:103], v[32:47]
	v_exp_f32_e32 v129, v129
	v_exp_f32_e32 v113, v113
	ds_read_b64_tr_b16 v[88:89], v213 offset:4096
	ds_read_b64_tr_b16 v[90:91], v213 offset:6144
	s_waitcnt lgkmcnt(4)
	v_mfma_f32_32x32x16_bf16 v[48:63], v[96:99], v[80:83], v[48:63]
	v_exp_f32_e32 v130, v130
	v_exp_f32_e32 v114, v114
	v_add_f32_e32 v100, v113, v112
	v_add_f32_e32 v101, v129, v128
	ds_read_b64_tr_b16 v[80:81], v213 offset:4608
	ds_read_b64_tr_b16 v[82:83], v213 offset:6656
	s_waitcnt lgkmcnt(4)
	v_mfma_f32_32x32x16_bf16 v[64:79], v[96:99], v[84:87], v[64:79]
	v_exp_f32_e32 v131, v131
	v_exp_f32_e32 v115, v115
	v_add_f32_e32 v96, v114, v100
	v_add_f32_e32 v97, v130, v101
	ds_read_b64_tr_b16 v[84:85], v213 offset:5120
	ds_read_b64_tr_b16 v[86:87], v213 offset:7168
	s_waitcnt lgkmcnt(4)
	v_mfma_f32_32x32x16_bf16 v[16:31], v[10:13], v[88:91], v[16:31]
	v_exp_f32_e32 v132, v132
	v_exp_f32_e32 v116, v116
	v_add_f32_e32 v96, v115, v96
	v_add_f32_e32 v97, v131, v97
	s_add_u32 vcc_lo, s0, s30
	s_addc_u32 vcc_hi, s1, s31
	s_add_i32 s4, s62, s97
	s_mov_b32 m0, s4
	ds_read_b64_tr_b16 v[88:89], v213 offset:5632
	ds_read_b64_tr_b16 v[90:91], v213 offset:7680
	global_load_lds_dwordx4 v160, vcc
	s_waitcnt lgkmcnt(4)
	v_mfma_f32_32x32x16_bf16 v[32:47], v[10:13], v[80:83], v[32:47]
	v_exp_f32_e32 v133, v133
	v_exp_f32_e32 v117, v117
	v_add_f32_e32 v92, v116, v96
	v_add_f32_e32 v93, v132, v97
	ds_read_b64_tr_b16 v[80:81], v213 offset:8192
	ds_read_b64_tr_b16 v[82:83], v213 offset:10240
	s_waitcnt lgkmcnt(4)
	v_mfma_f32_32x32x16_bf16 v[48:63], v[10:13], v[84:87], v[48:63]
	v_exp_f32_e32 v134, v134
	v_exp_f32_e32 v118, v118
	v_add_f32_e32 v92, v117, v92
	v_add_f32_e32 v93, v133, v93
	s_add_i32 m0, s4, 0x2000
	ds_read_b64_tr_b16 v[84:85], v213 offset:8704
	ds_read_b64_tr_b16 v[86:87], v213 offset:10752
	global_load_lds_dwordx4 v14, vcc
	s_waitcnt lgkmcnt(4)
	v_mfma_f32_32x32x16_bf16 v[64:79], v[10:13], v[88:91], v[64:79]
	v_exp_f32_e32 v135, v135
	v_exp_f32_e32 v119, v119
	v_add_f32_e32 v88, v118, v92
	v_add_f32_e32 v89, v134, v93
	ds_read_b64_tr_b16 v[10:11], v213 offset:9216
	ds_read_b64_tr_b16 v[12:13], v213 offset:11264
	s_waitcnt lgkmcnt(4)
	v_mfma_f32_32x32x16_bf16 v[16:31], v[6:9], v[80:83], v[16:31]
	v_exp_f32_e32 v136, v136
	v_exp_f32_e32 v120, v120
	v_add_f32_e32 v88, v119, v88
	v_add_f32_e32 v89, v135, v89
	ds_read_b64_tr_b16 v[80:81], v213 offset:9728
	ds_read_b64_tr_b16 v[82:83], v213 offset:11776
	s_waitcnt lgkmcnt(4)
	v_mfma_f32_32x32x16_bf16 v[32:47], v[6:9], v[84:87], v[32:47]
	v_exp_f32_e32 v137, v137
	v_exp_f32_e32 v121, v121
	v_add_f32_e32 v84, v120, v88
	v_add_f32_e32 v85, v136, v89
	ds_read_b64_tr_b16 v[88:89], v213 offset:12288
	ds_read_b64_tr_b16 v[90:91], v213 offset:14336
	s_waitcnt lgkmcnt(4)
	v_mfma_f32_32x32x16_bf16 v[48:63], v[6:9], v[10:13], v[48:63]
	v_exp_f32_e32 v138, v138
	v_exp_f32_e32 v122, v122
	v_add_f32_e32 v10, v121, v84
	v_add_f32_e32 v11, v137, v85
	ds_read_b64_tr_b16 v[92:93], v213 offset:12800
	ds_read_b64_tr_b16 v[94:95], v213 offset:14848
	s_waitcnt lgkmcnt(4)
	v_mfma_f32_32x32x16_bf16 v[64:79], v[6:9], v[80:83], v[64:79]
	v_exp_f32_e32 v139, v139
	v_exp_f32_e32 v123, v123
	v_add_f32_e32 v6, v122, v10
	v_add_f32_e32 v7, v138, v11
	v_add_u32_e32 v8, s18, v209
	ds_read_b64_tr_b16 v[96:97], v213 offset:13312
	ds_read_b64_tr_b16 v[98:99], v213 offset:15360
	ds_read_b128 v[80:83], v8
	ds_read_b128 v[84:87], v8 offset:4096
	s_waitcnt lgkmcnt(6)
	v_mfma_f32_32x32x16_bf16 v[16:31], v[2:5], v[88:91], v[16:31]
	v_exp_f32_e32 v140, v140
	v_exp_f32_e32 v124, v124
	v_add_f32_e32 v100, v123, v6
	v_add_f32_e32 v101, v139, v7
	v_add_u32_e32 v10, s18, v210
	ds_read_b64_tr_b16 v[88:89], v213 offset:13824
	ds_read_b64_tr_b16 v[90:91], v213 offset:15872
	ds_read_b128 v[6:9], v10
	ds_read_b128 v[10:13], v10 offset:4096
	s_waitcnt lgkmcnt(8)
	v_mfma_f32_32x32x16_bf16 v[32:47], v[2:5], v[92:95], v[32:47]
	v_exp_f32_e32 v141, v141
	v_exp_f32_e32 v125, v125
	v_add_f32_e32 v92, v124, v100
	v_add_f32_e32 v93, v140, v101
	s_waitcnt lgkmcnt(6)
	v_mfma_f32_32x32x16_bf16 v[48:63], v[2:5], v[96:99], v[48:63]
	v_exp_f32_e32 v142, v142
	v_exp_f32_e32 v126, v126
	v_add_f32_e32 v92, v125, v92
	v_add_f32_e32 v93, v141, v93
	s_waitcnt lgkmcnt(2)
	v_mfma_f32_32x32x16_bf16 v[64:79], v[2:5], v[88:91], v[64:79]
	v_exp_f32_e32 v143, v143
	v_exp_f32_e32 v127, v127
	v_add_f32_e32 v2, v126, v92
	v_add_f32_e32 v3, v142, v93
	s_nop 0
	v_add_f32_e32 v3, v143, v3
	v_add_f32_e32 v2, v127, v2
	v_add_f32_e32 v213, v3, v2
	v_mov_b32_e32 v214, v213
	s_nop 1
	v_permlane32_swap_b32_e32 v213, v214
	v_cmp_neq_f32_e32 vcc, 1.0, v0
	s_cbranch_vccz .LBB0_323
	s_and_saveexec_b64 s[4:5], s[46:47]
	ds_write_b32 v188, v0 offset:128
	s_or_b64 exec, exec, s[4:5]
	s_waitcnt lgkmcnt(0)
	v_add_u32_e32 v96, s2, v170
	ds_read_b128 v[2:5], v96 offset:224
	ds_read_b128 v[88:91], v96 offset:192
	ds_read_b128 v[92:95], v96 offset:160
	ds_read_b128 v[96:99], v96 offset:128
	s_waitcnt lgkmcnt(0)
	v_pk_mul_f32 v[28:29], v[28:29], v[2:3]
	v_pk_mul_f32 v[24:25], v[24:25], v[88:89]
	v_pk_mul_f32 v[20:21], v[20:21], v[92:93]
	v_pk_mul_f32 v[30:31], v[30:31], v[4:5]
	v_pk_mul_f32 v[26:27], v[26:27], v[90:91]
	v_pk_mul_f32 v[22:23], v[22:23], v[94:95]
	v_pk_mul_f32 v[18:19], v[18:19], v[98:99]
	v_pk_mul_f32 v[16:17], v[16:17], v[96:97]
	v_pk_mul_f32 v[44:45], v[44:45], v[2:3]
	v_pk_mul_f32 v[40:41], v[40:41], v[88:89]
	v_pk_mul_f32 v[36:37], v[36:37], v[92:93]
	v_pk_mul_f32 v[46:47], v[46:47], v[4:5]
	v_pk_mul_f32 v[42:43], v[42:43], v[90:91]
	v_pk_mul_f32 v[38:39], v[38:39], v[94:95]
	v_pk_mul_f32 v[34:35], v[34:35], v[98:99]
	v_pk_mul_f32 v[32:33], v[32:33], v[96:97]
	v_pk_mul_f32 v[60:61], v[60:61], v[2:3]
	v_pk_mul_f32 v[56:57], v[56:57], v[88:89]
	v_pk_mul_f32 v[52:53], v[52:53], v[92:93]
	v_pk_mul_f32 v[62:63], v[62:63], v[4:5]
	v_pk_mul_f32 v[58:59], v[58:59], v[90:91]
	v_pk_mul_f32 v[54:55], v[54:55], v[94:95]
	v_pk_mul_f32 v[50:51], v[50:51], v[98:99]
	v_pk_mul_f32 v[48:49], v[48:49], v[96:97]
	v_pk_mul_f32 v[76:77], v[76:77], v[2:3]
	v_pk_mul_f32 v[72:73], v[72:73], v[88:89]
	v_pk_mul_f32 v[68:69], v[68:69], v[92:93]
	v_pk_mul_f32 v[78:79], v[78:79], v[4:5]
	v_pk_mul_f32 v[74:75], v[74:75], v[90:91]
	v_pk_mul_f32 v[70:71], v[70:71], v[94:95]
	v_pk_mul_f32 v[66:67], v[66:67], v[98:99]
	v_pk_mul_f32 v[64:65], v[64:65], v[96:97]

; #define VRD_(S, I) do { vl[S] = vtr(vp + v_rd_off((I) & 3, (I) >> 2, 0)); vh[S] = vtr(vp + v_rd_off((I) & 3, (I) >> 2, 1)); } while (0)
; template <int DK, bool NOMAX> ...
;     ...
; #pragma unroll
;   for (int i = 0; i < 16; ++i) {
;     if (i + 2 < 16) VRD_((i + 2) % 3, i + 2);
;     if (i == 1) { if (dk) __builtin_amdgcn_global_load_lds((const unsigned*)gk0, lk, 16, 0, 0); }
;     if (i == 3) { if constexpr (DK == 128) { if (dk) __builtin_amdgcn_global_load_lds((const unsigned*)gk1, (lds_up)((lds_cp)lk + 8192), 16, 0, 0); } }
;     if (i == 5) { if (dv) __builtin_amdgcn_global_load_lds((const unsigned*)gv0, lv, 16, 0, 0); }
;     if (i == 7) { if (dv) __builtin_amdgcn_global_load_lds((const unsigned*)gv1, (lds_up)((lds_cp)lv + 8192), 16, 0, 0); }
.LBB0_331:
	s_or_b64 exec, exec, s[4:5]
	s_cmp_gt_u32 s96, 59
	s_cselect_b64 s[4:5], -1, 0
	ds_read_b64_tr_b16 v[112:113], v217 offset:1024
	ds_read_b64_tr_b16 v[114:115], v217 offset:3072
	s_waitcnt lgkmcnt(4)
	v_mfma_f32_32x32x16_bf16 v[16:31], v[128:131], v[136:139], v[16:31]
	v_exp_f32_e32 v96, v96
	v_exp_f32_e32 v80, v80
	ds_read_b64_tr_b16 v[116:117], v217 offset:1536
	ds_read_b64_tr_b16 v[118:119], v217 offset:3584
	s_and_b64 vcc, exec, s[4:5]
	s_cbranch_vccnz .LBB0_333
	s_add_u32 vcc_lo, s0, s34
	s_addc_u32 vcc_hi, s1, s35
	s_add_i32 m0, s3, s59
	s_nop 0
	global_load_lds_dwordx4 v162, vcc
; template <int DK, bool NOMAX> ...
;     ...
; #pragma unroll
;   for (int i = 0; i < 16; ++i) {
;     if (i + 2 < 16) VRD_((i + 2) % 3, i + 2);
;     if (i == 1) { if (dk) __builtin_amdgcn_global_load_lds((const unsigned*)gk0, lk, 16, 0, 0); }
;     if (i == 3) { if constexpr (DK == 128) { if (dk) __builtin_amdgcn_global_load_lds((const unsigned*)gk1, (lds_up)((lds_cp)lk + 8192), 16, 0, 0); } }
;     if (i == 5) { if (dv) __builtin_amdgcn_global_load_lds((const unsigned*)gv0, lv, 16, 0, 0); }
;     if (i == 7) { if (dv) __builtin_amdgcn_global_load_lds((const unsigned*)gv1, (lds_up)((lds_cp)lv + 8192), 16, 0, 0); }
;     if (i == 12 || i == 13) { const int cb_ = ((i - 12) * 16 + hi * 8) * 2;
;       if constexpr (DK == 128) { kf[i - 12][0] = *reinterpret_cast<const bf16x8*>(Kn + KSWZ128(r32, cb_)); kf[i - 12][1] = *reinterpret_cast<const bf16x8*>(Kn + KSWZ128(32 + r32, cb_)); }
;       else { kf[i - 12][0] = *reinterpret_cast<const bf16x8*>(Kn + KSWZ64(r32, cb_)); kf[i - 12][1] = *reinterpret_cast<const bf16x8*>(Kn + KSWZ64(32 + r32, cb_)); } }
;     SBAR();
;     o[i & 3] = __builtin_amdgcn_mfma_f32_32x32x16_bf16(pa[i >> 2], VFR_(i % 3), o[i & 3], 0, 0, 0);
;     if constexpr (NOMAX) { c0[i] = __builtin_amdgcn_exp2f(c0[i]); c1[i] = __builtin_amdgcn_exp2f(c1[i]); if (i > 0) { psa += c0[i - 1]; psb += c1[i - 1]; } PIN(c0); PIN(c1); PIN(psa); PIN(psb); }
;     else {
;     if (i == 0) { ma = max3f(c0[0], c0[1], c1[0]); mb = max3f(c0[2], c0[3], c1[1]); ma = max3f(ma, c1[2], c1[3]); }
;     if (i >= 1 && i <= 3) { const int r = 4 * i; ma = max3f(ma, c0[r], c0[r + 1]); mb = max3f(mb, c0[r + 2], c0[r + 3]); ma = max3f(ma, c1[r], c1[r + 1]); mb = max3f(mb, c1[r + 2], c1[r + 3]); }
;     if (i == 4) { float pmax = fmaxf(ma, mb);
;       { auto rr = __builtin_amdgcn_permlane32_swap(__float_as_uint(pmax), __float_as_uint(pmax), false, false);
;         pmax = fmaxf(__uint_as_float(rr[0]), __uint_as_float(rr[1])); }
;       pmax += cb;
;       const bool keep = __all(pmax - m_reg <= THR2);
;       const float mn = keep ? m_reg : fmaxf(m_reg, pmax);
;       alpha = __builtin_amdgcn_exp2f(m_reg - mn); m_reg = mn; mnC = cb - mn; }
;     if (i >= 5 && i <= 8) { const int r = 4 * (i - 5);
; #pragma unroll
;       for (int q = 0; q < 4; ++q) { c0[r + q] += mnC; c1[r + q] += mnC; } }
;     if (i >= 9) { const int r0 = (i - 9) * 2 + (i > 14 ? 1 : 0), n = i >= 14 ? 3 : 2;
.LBB0_333:
	v_sub_f32_e32 v120, v215, v212
	v_exp_f32_e32 v120, v120
	s_add_i32 s18, s63, 0xffffc000
	s_and_b32 s18, s18, 0xc000
	s_add_i32 s18, s18, 0
	s_waitcnt lgkmcnt(4)
	v_mfma_f32_32x32x16_bf16 v[32:47], v[128:131], v[132:135], v[32:47]
	v_exp_f32_e32 v97, v97
	v_exp_f32_e32 v81, v81
	ds_read_b64_tr_b16 v[122:123], v217 offset:4096
	ds_read_b64_tr_b16 v[124:125], v217 offset:6144
	s_waitcnt lgkmcnt(4)
	v_mfma_f32_32x32x16_bf16 v[48:63], v[128:131], v[112:115], v[48:63]
	v_exp_f32_e32 v98, v98
	v_exp_f32_e32 v82, v82
	v_add_f32_e32 v132, v81, v80
	v_add_f32_e32 v121, v97, v96
	ds_read_b64_tr_b16 v[112:113], v217 offset:4608
	ds_read_b64_tr_b16 v[114:115], v217 offset:6656
	s_waitcnt lgkmcnt(4)
	v_mfma_f32_32x32x16_bf16 v[64:79], v[128:131], v[116:119], v[64:79]
	v_exp_f32_e32 v99, v99
	v_exp_f32_e32 v83, v83
	v_add_f32_e32 v128, v82, v132
	v_add_f32_e32 v121, v98, v121
	ds_read_b64_tr_b16 v[116:117], v217 offset:5120
	ds_read_b64_tr_b16 v[118:119], v217 offset:7168
	s_waitcnt lgkmcnt(4)
	v_mfma_f32_32x32x16_bf16 v[16:31], v[10:13], v[122:125], v[16:31]
	v_exp_f32_e32 v100, v100
	v_exp_f32_e32 v84, v84
	v_add_f32_e32 v128, v83, v128
	v_add_f32_e32 v121, v99, v121
	s_add_u32 vcc_lo, s0, s36
	s_addc_u32 vcc_hi, s1, s37
	s_add_i32 s19, s62, s95
	s_mov_b32 m0, s19
	ds_read_b64_tr_b16 v[122:123], v217 offset:5632
	ds_read_b64_tr_b16 v[124:125], v217 offset:7680
	global_load_lds_dwordx4 v160, vcc
	s_waitcnt lgkmcnt(4)
	v_mfma_f32_32x32x16_bf16 v[32:47], v[10:13], v[112:115], v[32:47]
	v_exp_f32_e32 v101, v101
	v_exp_f32_e32 v85, v85
	v_add_f32_e32 v126, v84, v128
	v_add_f32_e32 v121, v100, v121
	ds_read_b64_tr_b16 v[112:113], v217 offset:8192
	ds_read_b64_tr_b16 v[114:115], v217 offset:10240
	s_waitcnt lgkmcnt(4)
	v_mfma_f32_32x32x16_bf16 v[48:63], v[10:13], v[116:119], v[48:63]
	v_exp_f32_e32 v102, v102
	v_exp_f32_e32 v86, v86
	v_add_f32_e32 v126, v85, v126
	v_add_f32_e32 v121, v101, v121
	s_add_i32 m0, s19, 0x2000
	ds_read_b64_tr_b16 v[116:117], v217 offset:8704
	ds_read_b64_tr_b16 v[118:119], v217 offset:10752
	global_load_lds_dwordx4 v14, vcc
	s_waitcnt lgkmcnt(4)
	v_mfma_f32_32x32x16_bf16 v[64:79], v[10:13], v[122:125], v[64:79]
	v_exp_f32_e32 v103, v103
	v_exp_f32_e32 v87, v87
	v_add_f32_e32 v122, v86, v126
	v_add_f32_e32 v121, v102, v121
	ds_read_b64_tr_b16 v[10:11], v217 offset:9216
	ds_read_b64_tr_b16 v[12:13], v217 offset:11264
	s_waitcnt lgkmcnt(4)
	v_mfma_f32_32x32x16_bf16 v[16:31], v[6:9], v[112:115], v[16:31]
	v_exp_f32_e32 v104, v104
	v_exp_f32_e32 v88, v88
	v_add_f32_e32 v122, v87, v122
	v_add_f32_e32 v121, v103, v121
	ds_read_b64_tr_b16 v[112:113], v217 offset:9728
	ds_read_b64_tr_b16 v[114:115], v217 offset:11776
	s_waitcnt lgkmcnt(4)
	v_mfma_f32_32x32x16_bf16 v[32:47], v[6:9], v[116:119], v[32:47]
	v_exp_f32_e32 v105, v105
	v_exp_f32_e32 v89, v89
	v_add_f32_e32 v116, v88, v122
	v_add_f32_e32 v117, v104, v121
	ds_read_b64_tr_b16 v[122:123], v217 offset:12288
	ds_read_b64_tr_b16 v[124:125], v217 offset:14336
	s_waitcnt lgkmcnt(4)
	v_mfma_f32_32x32x16_bf16 v[48:63], v[6:9], v[10:13], v[48:63]
	v_exp_f32_e32 v106, v106
	v_exp_f32_e32 v90, v90
	v_add_f32_e32 v10, v89, v116
	v_add_f32_e32 v11, v105, v117
	ds_read_b64_tr_b16 v[126:127], v217 offset:12800
	ds_read_b64_tr_b16 v[128:129], v217 offset:14848
	s_waitcnt lgkmcnt(4)
	v_mfma_f32_32x32x16_bf16 v[64:79], v[6:9], v[112:115], v[64:79]
	v_exp_f32_e32 v107, v107
	v_exp_f32_e32 v91, v91
	v_add_f32_e32 v6, v90, v10
	v_add_f32_e32 v7, v106, v11
	v_add_u32_e32 v8, s18, v209
	ds_read_b64_tr_b16 v[130:131], v217 offset:13312
	ds_read_b64_tr_b16 v[132:133], v217 offset:15360
	ds_read_b128 v[116:119], v8
	ds_read_b128 v[112:115], v8 offset:4096
	s_waitcnt lgkmcnt(6)
	v_mfma_f32_32x32x16_bf16 v[16:31], v[2:5], v[122:125], v[16:31]
	v_exp_f32_e32 v108, v108
	v_exp_f32_e32 v92, v92
	v_add_f32_e32 v121, v91, v6
	v_add_f32_e32 v134, v107, v7
	v_add_u32_e32 v6, s18, v210
	ds_read_b64_tr_b16 v[122:123], v217 offset:13824
	ds_read_b64_tr_b16 v[124:125], v217 offset:15872
	ds_read_b128 v[10:13], v6
	ds_read_b128 v[6:9], v6 offset:4096
	s_waitcnt lgkmcnt(8)
	v_mfma_f32_32x32x16_bf16 v[32:47], v[2:5], v[126:129], v[32:47]
	v_exp_f32_e32 v109, v109
	v_exp_f32_e32 v93, v93
	v_add_f32_e32 v121, v92, v121
	v_add_f32_e32 v126, v108, v134
	s_waitcnt lgkmcnt(6)
	v_mfma_f32_32x32x16_bf16 v[48:63], v[2:5], v[130:133], v[48:63]
	v_exp_f32_e32 v110, v110
	v_exp_f32_e32 v94, v94
	v_add_f32_e32 v121, v93, v121
	v_add_f32_e32 v126, v109, v126
	s_waitcnt lgkmcnt(2)
	v_mfma_f32_32x32x16_bf16 v[64:79], v[2:5], v[122:125], v[64:79]
	v_exp_f32_e32 v111, v111
	v_exp_f32_e32 v95, v95
	v_add_f32_e32 v2, v94, v121
	v_add_f32_e32 v3, v110, v126
	s_nop 0
	v_add_f32_e32 v3, v111, v3
	v_add_f32_e32 v2, v95, v2
	v_add_f32_e32 v2, v3, v2
	v_mov_b32_e32 v3, v2
	s_nop 1
	v_permlane32_swap_b32_e32 v2, v3
	v_cmp_neq_f32_e32 vcc, 1.0, v120
	s_cbranch_vccz .LBB0_337
	s_and_saveexec_b64 s[18:19], s[46:47]
	ds_write_b32 v188, v120 offset:128
	s_or_b64 exec, exec, s[18:19]
	s_waitcnt lgkmcnt(0)
	v_add_u32_e32 v4, s2, v170
	ds_read_b128 v[122:125], v4 offset:224
	ds_read_b128 v[126:129], v4 offset:192
	ds_read_b128 v[130:133], v4 offset:160
	ds_read_b128 v[134:137], v4 offset:128
	s_waitcnt lgkmcnt(0)
	v_pk_mul_f32 v[28:29], v[28:29], v[122:123]
	v_pk_mul_f32 v[24:25], v[24:25], v[126:127]
	v_pk_mul_f32 v[20:21], v[20:21], v[130:131]
	v_pk_mul_f32 v[30:31], v[30:31], v[124:125]
	v_pk_mul_f32 v[26:27], v[26:27], v[128:129]
	v_pk_mul_f32 v[22:23], v[22:23], v[132:133]
	v_pk_mul_f32 v[18:19], v[18:19], v[136:137]
	v_pk_mul_f32 v[16:17], v[16:17], v[134:135]
	v_pk_mul_f32 v[44:45], v[44:45], v[122:123]
	v_pk_mul_f32 v[40:41], v[40:41], v[126:127]
	v_pk_mul_f32 v[36:37], v[36:37], v[130:131]
	v_pk_mul_f32 v[46:47], v[46:47], v[124:125]
	v_pk_mul_f32 v[42:43], v[42:43], v[128:129]
	v_pk_mul_f32 v[38:39], v[38:39], v[132:133]
	v_pk_mul_f32 v[34:35], v[34:35], v[136:137]
	v_pk_mul_f32 v[32:33], v[32:33], v[134:135]
	v_pk_mul_f32 v[60:61], v[60:61], v[122:123]
	v_pk_mul_f32 v[56:57], v[56:57], v[126:127]
	v_pk_mul_f32 v[52:53], v[52:53], v[130:131]
	v_pk_mul_f32 v[62:63], v[62:63], v[124:125]
	v_pk_mul_f32 v[58:59], v[58:59], v[128:129]
	v_pk_mul_f32 v[54:55], v[54:55], v[132:133]
	v_pk_mul_f32 v[50:51], v[50:51], v[136:137]
	v_pk_mul_f32 v[48:49], v[48:49], v[134:135]
	v_pk_mul_f32 v[76:77], v[76:77], v[122:123]
	v_pk_mul_f32 v[72:73], v[72:73], v[126:127]
	v_pk_mul_f32 v[68:69], v[68:69], v[130:131]
	v_pk_mul_f32 v[78:79], v[78:79], v[124:125]
	v_pk_mul_f32 v[74:75], v[74:75], v[128:129]
	v_pk_mul_f32 v[70:71], v[70:71], v[132:133]
	v_pk_mul_f32 v[66:67], v[66:67], v[136:137]
	v_pk_mul_f32 v[64:65], v[64:65], v[134:135]
